# attention online softmax: lazy-rescale threshold raised from 8 to 16 (log2 units), fewer accumulator rescales; same math
# speedup vs baseline: 1.0004x; 1.0004x over previous
; #define LAS __attribute__((address_space(3)))
; __device__ __forceinline__ int v_st(int k, int c) { const int kk = (k & ~0xC) | ((k & 4) << 1) | ((k & 8) >> 1); return ((kk >> 3) * 4 + (c >> 5)) * 512 + ((kk & 7) * 32 + (c & 31)) * 2; }
; __device__ __forceinline__ void attn_block(const Ptrs& P, int b, int h, int qb, LAS char* lds) {
;     const int tid = threadIdx.x, wid = __builtin_amdgcn_readfirstlane(tid >> 6), lane = tid & 63, r32 = lane & 31, hi = lane >> 5;
;     const int grp = wid >> 2;
;     const int i0 = qb * QB, P0 = NMETA + i0;
;     const int NT = (P0 + QB - 1) / KVBLK + 1;
;     const bf16* Qw = P.q_() + ((size_t)(b * NH + h) * SEQ + i0 + wid * QBLK + r32) * DQK;
;     const __amdgpu_buffer_rsrc_t srdK = __builtin_amdgcn_make_buffer_rsrc((void*)(P.kn_() + (size_t)(b * NH + h) * LPAD * 128), (short)0, LPAD * 256, 0x00020000);
;     const __amdgpu_buffer_rsrc_t srdV = __builtin_amdgcn_make_buffer_rsrc((void*)(P.v_() + (size_t)(b * NH + h) * LPAD * 128), (short)0, LPAD * 256, 0x00020000);
;     const __amdgpu_buffer_rsrc_t srdR = __builtin_amdgcn_make_buffer_rsrc((void*)(P.kr_() + (size_t)b * LPAD * 64), (short)0, LPAD * 128, 0x00020000);
;     bf16x8 qr[12];
; #pragma unroll
;     for (int d0 = 0; d0 < 12; ++d0) qr[d0] = *(const bf16x8*)(Qw + d0 * 16 + hi * 8);
;     const int sr = tid >> 4, sc = (tid & 15) * 8, kws = OFF_K + KSWZ(sr, sc * 2), vst0 = OFF_V + v_st(sr, sc), vst1 = OFF_V + v_st(32 + sr, sc);
;     const int rr = tid >> 3, rc = tid & 7, rws = OFF_R + RSWZ(rr, rc);
;     const int qlo = P0 + wid * QBLK, qm = qlo + r32 - 4 * hi;
;     LAS float* wsf = (LAS float*)(lds + OFF_WS) + wid * 64; LAS float* li_l = wsf; LAS float* al_l = wsf + 32;
;     const int lbase = (int)(uintptr_t)(lds);
;     const int vb0 = lbase + OFF_V + v_rd_base(lane);
;     int kbase = lbase + OFF_K + KSWZ(r32, (hi * 8) * 2), rbase = lbase + OFF_R + RSWZ(r32, hi);
;     float m_reg = -1e30f, l_reg = 0.f; f32x16 o[4] = {};
;     bf16x8 st_k0, st_k1, st_v0, st_v1, st_r;
;     const unsigned gofk = (unsigned)((tid >> 4) * 128 + (tid & 15) * 8) * 2u, gofr = (unsigned)((tid >> 3) * 64 + (tid & 7) * 8) * 2u;
;     ...
;         if (!__all(pmax - m_reg <= THRL)) { const float mn = fmaxf(m_reg, pmax); alpha = __builtin_amdgcn_exp2f(m_reg - mn); m_reg = mn; }
.LBB0_607:
	s_andn2_b64 vcc, exec, s[8:9]
	s_waitcnt vmcnt(0)
	s_barrier
	s_cbranch_vccnz .LBB0_634
	v_lshrrev_b32_e32 v3, 5, v1
	v_mov_b32_e32 v2, 0
	v_lshlrev_b32_e32 v4, 4, v3
	v_mov_b32_e32 v5, v2
	v_lshl_add_u64 v[4:5], s[86:87], 0, v[4:5]
	s_mov_b64 s[0:1], 0x9100000
	v_lshrrev_b32_e32 v9, 3, v0
	v_lshl_add_u64 v[168:169], v[4:5], 0, s[0:1]
	v_lshrrev_b32_e32 v4, 4, v0
	v_lshlrev_b32_e32 v5, 3, v0
	v_and_b32_e32 v9, 8, v9
	v_and_b32_e32 v6, 0x78, v5
	v_lshlrev_b32_e32 v7, 8, v4
	v_and_or_b32 v10, v4, 16, v9
	v_or_b32_e32 v4, 32, v4
	v_lshlrev_b32_e32 v6, 1, v6
	v_bfe_u32 v12, v0, 4, 2
	v_and_or_b32 v4, v4, 48, v9
	s_add_u32 s3, s86, 0xc100000
	v_lshrrev_b32_e32 v10, 1, v10
	v_bfe_u32 v11, v5, 5, 2
	v_and_or_b32 v12, v28, 4, v12
	v_and_b32_e32 v13, 48, v6
	v_lshrrev_b32_e32 v4, 1, v4
	s_addc_u32 s33, s87, 0
	v_or_b32_e32 v10, v10, v11
	v_lshl_or_b32 v12, v12, 6, v13
	v_or_b32_e32 v4, v4, v11
	s_add_u32 s35, s86, 0xe200000
	v_lshl_or_b32 v175, v10, 9, v12
	v_lshl_or_b32 v176, v4, 9, v12
	v_lshrrev_b32_e32 v175, 7, v0
	v_bfe_u32 v176, v0, 2, 2
	v_lshl_or_b32 v175, v175, 2, v176
	v_bfe_u32 v176, v0, 4, 3
	v_lshlrev_b32_e32 v176, 6, v176
	v_and_b32_e32 v250, 3, v0
	v_lshl_or_b32 v176, v250, 4, v176
	v_lshl_or_b32 v175, v175, 9, v176
	v_add_u32_e32 v176, 0x2000, v175
	v_lshlrev_b32_e32 v177, 4, v0
	s_movk_i32 s0, 0x70
	v_lshlrev_b32_e32 v12, 1, v0
	s_addc_u32 s58, s87, 0
	v_bitop3_b32 v4, v177, s0, v0 bitop3:0x48
	s_movk_i32 s0, 0x1f80
	v_and_b32_e32 v11, 0xc0, v177
	v_and_b32_e32 v12, 32, v12
	v_and_b32_e32 v5, 0x118, v5
	s_add_u32 s59, s86, 0x8f00000
	v_and_or_b32 v4, v177, s0, v4
	v_or3_b32 v5, v12, v11, v5
	v_bitop3_b32 v12, v3, v0, 15 bitop3:0x78
	v_lshrrev_b32_e32 v14, 1, v0
	s_addc_u32 s60, s87, 0
	v_lshlrev_b32_e32 v11, 8, v174
	v_bitop3_b32 v14, v3, v14, 7 bitop3:0x78
	v_add_u32_e32 v180, 0, v4
	v_lshlrev_b32_e32 v181, 2, v3
	s_add_i32 s1, 0, 0xc000
	v_lshlrev_b32_e32 v3, 4, v12
	v_and_b32_e32 v4, 30, v0
	v_and_b32_e32 v8, 0xf0, v0
	v_lshlrev_b32_e32 v13, 7, v174
	s_add_i32 s0, 0, 0x8000
	v_add_u32_e32 v182, s1, v5
	v_add3_u32 v183, v11, 0, v3
	v_lshlrev_b32_e32 v3, 4, v14
	v_lshlrev_b32_e32 v4, 1, v4
	v_mov_b32_e32 v5, v2
	v_bitop3_b32 v8, v6, v7, v8 bitop3:0xde
	v_or_b32_e32 v10, 0xc000, v175
	v_or_b32_e32 v9, 0xc000, v176
	v_add3_u32 v184, v13, s0, v3
	v_and_b32_e32 v3, 1, v0
	v_lshl_add_u64 v[4:5], s[86:87], 0, v[4:5]
	s_mov_b64 s[8:9], 0x4500000
	s_mov_b32 s11, 0x20000
	s_mov_b32 s7, 0
	s_mov_b32 s61, 0x8000
	v_or_b32_e32 v178, v6, v7
	v_add_u32_e32 v179, 0, v8
	v_cmp_gt_u32_e64 s[0:1], 32, v1
	v_cmp_eq_u32_e64 s[4:5], 0, v3
	v_lshl_add_u64 v[170:171], v[4:5], 0, s[8:9]
	v_or_b32_e32 v185, v181, v3
	v_sub_u32_e32 v186, v174, v181
	s_mov_b32 s10, 0x104000
	s_mov_b32 s18, 0x82000
	s_mov_b32 s19, s11
	s_movk_i32 s62, 0x180
	s_movk_i32 s63, 0x2000
	v_add_u32_e32 v187, 0, v175
	v_add_u32_e32 v188, 0, v176
	s_movk_i32 s64, 0x4000
	s_movk_i32 s65, 0x6000
	v_add_u32_e32 v189, 0, v10
	v_add_u32_e32 v190, 0, v9
	s_mov_b32 s66, 0xa000
	s_mov_b32 s67, 0x18000
	s_mov_b32 s68, 0x41800000
	s_mov_b32 s69, 0x10000
	s_mov_b32 s70, 0x12000
	s_mov_b32 s71, 0x1a000
	v_mov_b32_e32 v191, 0xff800000
	s_branch .LBB0_610
